# GLU epilogue: all 8 gate loads issued up front into dead operand VGPRs, per-item store-drain waits removed (on top of v19)
# baseline (speedup 1.0000x reference)
; __device__ __forceinline__ float sigmoidf_(float x) { return rcp_nr(1.f + __expf(fminf(-x, 80.f))); }
; __device__ __forceinline__ u32x2 pk4(f32x4 v) { u32x2 r; r.x = pk2(v.x, v.y); r.y = pk2(v.z, v.w); return r; }
; __device__ __forceinline__ f32x4 unpk4(u32x2 w) { f32x4 r; r.x = bflo(w.x); r.y = bfhi(w.x); r.z = bflo(w.y); r.w = bfhi(w.y); return r; }
; template <int EPI>
; __device__ __forceinline__ void epilogue(const Params& p, f32x4 (&acc)[2][2][4][2], const int pm, const int pn, const int wr, const int wc, const int fr, const int fq) {
;     ...
;     bf16_t* Mg = (bf16_t*)(ws + OFF_MG);
; #pragma unroll
;     for (int ai = 0; ai < 2; ++ai)
; #pragma unroll
;       for (int m = 0; m < 4; ++m) {
;         const int row = pm * 256 + ai * 128 + wr * 64 + m * 16 + fr;
;         const int j0 = pn * 128 + wc * 32 + fq * 8;
;         const u32x4 gw4 = *(const u32x4*)(P + (size_t)row * PW + 1024 + j0);
;         u32x2 o[2];
; #pragma unroll
;         for (int bj = 0; bj < 2; ++bj) {
;           const f32x4 ya = acc[ai][bj][m][0], yb = acc[ai][bj][m][1];
;           const f32x4 gs = unpk4(bj == 0 ? u32x2{gw4.x, gw4.y} : u32x2{gw4.z, gw4.w});
;           f32x4 sv;
;           sv.x = gs.x * ya.x * sigmoidf_(yb.x); sv.y = gs.y * ya.y * sigmoidf_(yb.y);
;           sv.z = gs.z * ya.z * sigmoidf_(yb.z); sv.w = gs.w * ya.w * sigmoidf_(yb.w);
;           o[bj] = pk4(sv);
;         }
;         *(u32x4*)(Mg + (size_t)row * DM + j0) = u32x4{o[0].x, o[0].y, o[1].x, o[1].y};
.LBB0_662:
	v_readlane_b32 s28, v244, 0
	v_lshl_or_b32 v142, s6, 7, v157
	v_readlane_b32 s30, v244, 2
	v_readlane_b32 s31, v244, 3
	v_lshl_add_u32 v144, s4, 8, v150
	v_ashrrev_i32_e32 v143, 31, v142
	v_mov_b64_e32 v[146:147], s[30:31]
	v_lshlrev_b64 v[142:143], 1, v[142:143]
	v_mad_i64_i32 v[148:149], s[26:27], v144, s50, v[146:147]
	v_lshl_add_u64 v[148:149], v[148:149], 0, v[142:143]
	global_load_dwordx4 v[162:165], v[148:149], off offset:2048
	v_or_b32_e32 v170, 16, v144
	v_mad_i64_i32 v[148:149], s[26:27], v170, s50, v[146:147]
	v_lshl_add_u64 v[148:149], v[148:149], 0, v[142:143]
	global_load_dwordx4 v[166:169], v[148:149], off offset:2048
	s_mov_b32 s99, 0
	s_mov_b32 s98, 0x18000
	v_lshl_add_u64 v[220:221], v[148:149], 0, s[98:99]
	global_load_dwordx4 v[196:199], v[220:221], off offset:2048
	s_mov_b32 s98, 0x30000
	v_lshl_add_u64 v[220:221], v[148:149], 0, s[98:99]
	global_load_dwordx4 v[200:203], v[220:221], off offset:2048
	s_mov_b32 s98, 0xa8000
	v_lshl_add_u64 v[220:221], v[148:149], 0, s[98:99]
	global_load_dwordx4 v[204:207], v[220:221], off offset:2048
	s_mov_b32 s98, 0xc0000
	v_lshl_add_u64 v[220:221], v[148:149], 0, s[98:99]
	global_load_dwordx4 v[208:211], v[220:221], off offset:2048
	s_mov_b32 s98, 0xd8000
	v_lshl_add_u64 v[220:221], v[148:149], 0, s[98:99]
	global_load_dwordx4 v[212:215], v[220:221], off offset:2048
	s_mov_b32 s98, 0xf0000
	v_lshl_add_u64 v[220:221], v[148:149], 0, s[98:99]
	global_load_dwordx4 v[216:219], v[220:221], off offset:2048
	v_max_f32_e64 v134, -v122, -v122
	v_max_f32_e64 v161, -v123, -v123
	v_max_f32_e64 v171, -v124, -v124
	v_max_f32_e64 v172, -v125, -v125
	v_max_f32_e64 v173, -v102, -v102
	v_max_f32_e64 v174, -v103, -v103
	v_max_f32_e64 v175, -v104, -v104
	v_min_f32_e32 v134, 0x42a00000, v134
	v_min_f32_e32 v149, 0x42a00000, v161
	v_max_f32_e64 v148, -v105, -v105
	v_min_f32_e32 v161, 0x42a00000, v171
	v_min_f32_e32 v171, 0x42a00000, v172
	v_min_f32_e32 v172, 0x42a00000, v173
	v_min_f32_e32 v173, 0x42a00000, v174
	v_min_f32_e32 v174, 0x42a00000, v175
	v_mul_f32_e32 v134, 0x3fb8aa3b, v134
	v_mul_f32_e32 v175, 0x3fb8aa3b, v149
	v_min_f32_e32 v148, 0x42a00000, v148
	v_mul_f32_e32 v161, 0x3fb8aa3b, v161
	v_mul_f32_e32 v171, 0x3fb8aa3b, v171
	v_mul_f32_e32 v176, 0x3fb8aa3b, v172
	v_mul_f32_e32 v177, 0x3fb8aa3b, v173
	v_exp_f32_e32 v172, v134
	v_exp_f32_e32 v173, v175
	v_mul_f32_e32 v178, 0x3fb8aa3b, v174
	v_mul_f32_e32 v179, 0x3fb8aa3b, v148
	v_exp_f32_e32 v174, v161
	v_exp_f32_e32 v175, v171
	v_exp_f32_e32 v176, v176
	v_exp_f32_e32 v177, v177
	v_exp_f32_e32 v178, v178
	v_exp_f32_e32 v179, v179
	v_pk_add_f32 v[172:173], v[172:173], 1.0 op_sel_hi:[1,0]
	v_pk_add_f32 v[174:175], v[174:175], 1.0 op_sel_hi:[1,0]
	v_rcp_f32_e32 v180, v172
	v_rcp_f32_e32 v181, v173
	v_pk_add_f32 v[176:177], v[176:177], 1.0 op_sel_hi:[1,0]
	v_pk_add_f32 v[178:179], v[178:179], 1.0 op_sel_hi:[1,0]
	v_rcp_f32_e32 v188, v174
	v_rcp_f32_e32 v189, v175
	v_rcp_f32_e32 v190, v176
	v_rcp_f32_e32 v191, v177
	v_rcp_f32_e32 v192, v178
	v_rcp_f32_e32 v193, v179
	v_pk_fma_f32 v[172:173], v[172:173], v[180:181], 1.0 op_sel_hi:[1,1,0] neg_lo:[1,0,0] neg_hi:[1,0,0]
	v_pk_fma_f32 v[174:175], v[174:175], v[188:189], 1.0 op_sel_hi:[1,1,0] neg_lo:[1,0,0] neg_hi:[1,0,0]
	v_pk_fma_f32 v[172:173], v[180:181], v[172:173], v[180:181]
	v_pk_fma_f32 v[176:177], v[176:177], v[190:191], 1.0 op_sel_hi:[1,1,0] neg_lo:[1,0,0] neg_hi:[1,0,0]
	v_pk_fma_f32 v[178:179], v[178:179], v[192:193], 1.0 op_sel_hi:[1,1,0] neg_lo:[1,0,0] neg_hi:[1,0,0]
	v_pk_fma_f32 v[174:175], v[188:189], v[174:175], v[188:189]
	v_ashrrev_i32_e32 v145, 31, v144
	v_pk_fma_f32 v[176:177], v[190:191], v[176:177], v[190:191]
	v_pk_fma_f32 v[178:179], v[192:193], v[178:179], v[192:193]
	v_max_f32_e64 v134, -v114, -v114
	v_lshl_add_u64 v[148:149], s[14:15], 0, v[142:143]
	v_min_f32_e32 v134, 0x42a00000, v134
	v_mul_f32_e32 v134, 0x3fb8aa3b, v134
	v_ashrrev_i32_e32 v171, 31, v170
	v_lshlrev_b64 v[170:171], 11, v[170:171]
	v_lshl_add_u64 v[170:171], v[148:149], 0, v[170:171]
	v_readlane_b32 s29, v244, 1
	s_waitcnt vmcnt(0)
	v_lshlrev_b32_e32 v180, 16, v162
	v_and_b32_e32 v181, 0xffff0000, v162
	v_lshlrev_b32_e32 v162, 16, v163
	v_and_b32_e32 v163, 0xffff0000, v163
	v_lshlrev_b32_e32 v188, 16, v164
	v_and_b32_e32 v189, 0xffff0000, v164
	v_lshlrev_b32_e32 v164, 16, v165
	v_and_b32_e32 v165, 0xffff0000, v165
	v_pk_mul_f32 v[180:181], v[126:127], v[180:181]
	v_pk_mul_f32 v[162:163], v[128:129], v[162:163]
	v_pk_mul_f32 v[188:189], v[110:111], v[188:189]
	v_pk_mul_f32 v[164:165], v[112:113], v[164:165]
	v_pk_mul_f32 v[172:173], v[172:173], v[180:181]
	v_pk_mul_f32 v[174:175], v[174:175], v[162:163]
	v_pk_mul_f32 v[176:177], v[176:177], v[188:189]
	v_pk_mul_f32 v[178:179], v[178:179], v[164:165]
	v_cvt_pk_bf16_f32 v162, v172, v173
	v_lshlrev_b64 v[172:173], 11, v[144:145]
	v_cvt_pk_bf16_f32 v163, v174, v175
	v_cvt_pk_bf16_f32 v164, v176, v177
	v_cvt_pk_bf16_f32 v165, v178, v179
	v_lshl_add_u64 v[172:173], v[148:149], 0, v[172:173]
	v_or_b32_e32 v176, 32, v144
	global_store_dwordx4 v[172:173], v[162:165], off
	v_exp_f32_e32 v172, v134
	v_max_f32_e64 v134, -v115, -v115
	v_mad_i64_i32 v[162:163], s[26:27], v176, s50, v[146:147]
	v_min_f32_e32 v134, 0x42a00000, v134
	v_lshl_add_u64 v[162:163], v[162:163], 0, v[142:143]
	v_mul_f32_e32 v134, 0x3fb8aa3b, v134
	v_mov_b32_e32 v162, v196
	v_mov_b32_e32 v163, v197
	v_mov_b32_e32 v164, v198
	v_mov_b32_e32 v165, v199
	v_exp_f32_e32 v173, v134
	v_max_f32_e64 v134, -v116, -v116
	v_min_f32_e32 v134, 0x42a00000, v134
	v_mul_f32_e32 v134, 0x3fb8aa3b, v134
	v_pk_add_f32 v[172:173], v[172:173], 1.0 op_sel_hi:[1,0]
	v_exp_f32_e32 v180, v134
	v_max_f32_e64 v134, -v117, -v117
; __device__ __forceinline__ float sigmoidf_(float x) { return rcp_nr(1.f + __expf(fminf(-x, 80.f))); }
; __device__ __forceinline__ u32x2 pk4(f32x4 v) { u32x2 r; r.x = pk2(v.x, v.y); r.y = pk2(v.z, v.w); return r; }
; __device__ __forceinline__ f32x4 unpk4(u32x2 w) { f32x4 r; r.x = bflo(w.x); r.y = bfhi(w.x); r.z = bflo(w.y); r.w = bfhi(w.y); return r; }
; template <int EPI>
; __device__ __forceinline__ void epilogue(const Params& p, f32x4 (&acc)[2][2][4][2], const int pm, const int pn, const int wr, const int wc, const int fr, const int fq) {
;     ...
;         for (int bj = 0; bj < 2; ++bj) {
;           const f32x4 ya = acc[ai][bj][m][0], yb = acc[ai][bj][m][1];
;           const f32x4 gs = unpk4(bj == 0 ? u32x2{gw4.x, gw4.y} : u32x2{gw4.z, gw4.w});
;           f32x4 sv;
;           sv.x = gs.x * ya.x * sigmoidf_(yb.x); sv.y = gs.y * ya.y * sigmoidf_(yb.y);
;           sv.z = gs.z * ya.z * sigmoidf_(yb.z); sv.w = gs.w * ya.w * sigmoidf_(yb.w);
;           o[bj] = pk4(sv);
;         }
;         *(u32x4*)(Mg + (size_t)row * DM + j0) = u32x4{o[0].x, o[0].y, o[1].x, o[1].y};
	v_rcp_f32_e32 v178, v172
	v_rcp_f32_e32 v179, v173
	v_min_f32_e32 v134, 0x42a00000, v134
	v_mul_f32_e32 v134, 0x3fb8aa3b, v134
	v_exp_f32_e32 v181, v134
	v_lshlrev_b32_e32 v174, 16, v166
	v_and_b32_e32 v175, 0xffff0000, v166
	v_pk_fma_f32 v[172:173], v[172:173], v[178:179], 1.0 op_sel_hi:[1,1,0] neg_lo:[1,0,0] neg_hi:[1,0,0]
	v_pk_mul_f32 v[174:175], v[118:119], v[174:175]
	v_pk_fma_f32 v[172:173], v[178:179], v[172:173], v[178:179]
	v_max_f32_e64 v134, -v86, -v86
	v_pk_mul_f32 v[172:173], v[172:173], v[174:175]
	v_pk_add_f32 v[174:175], v[180:181], 1.0 op_sel_hi:[1,0]
	v_lshlrev_b32_e32 v166, 16, v167
	v_rcp_f32_e32 v178, v174
	v_rcp_f32_e32 v179, v175
	v_and_b32_e32 v167, 0xffff0000, v167
	v_min_f32_e32 v134, 0x42a00000, v134
	v_pk_mul_f32 v[166:167], v[120:121], v[166:167]
	v_pk_fma_f32 v[174:175], v[174:175], v[178:179], 1.0 op_sel_hi:[1,1,0] neg_lo:[1,0,0] neg_hi:[1,0,0]
	v_mul_f32_e32 v134, 0x3fb8aa3b, v134
	v_pk_fma_f32 v[174:175], v[178:179], v[174:175], v[178:179]
	v_ashrrev_i32_e32 v177, 31, v176
	v_pk_mul_f32 v[174:175], v[174:175], v[166:167]
	v_cvt_pk_bf16_f32 v166, v172, v173
	v_exp_f32_e32 v172, v134
	v_max_f32_e64 v134, -v87, -v87
	v_min_f32_e32 v134, 0x42a00000, v134
	v_mul_f32_e32 v134, 0x3fb8aa3b, v134
	v_exp_f32_e32 v173, v134
	v_max_f32_e64 v134, -v88, -v88
	v_min_f32_e32 v134, 0x42a00000, v134
	v_mul_f32_e32 v134, 0x3fb8aa3b, v134
	v_pk_add_f32 v[172:173], v[172:173], 1.0 op_sel_hi:[1,0]
	v_exp_f32_e32 v180, v134
	v_max_f32_e64 v134, -v89, -v89
	v_rcp_f32_e32 v178, v172
	v_rcp_f32_e32 v179, v173
	v_min_f32_e32 v134, 0x42a00000, v134
	v_mul_f32_e32 v134, 0x3fb8aa3b, v134
	v_exp_f32_e32 v181, v134
	v_cvt_pk_bf16_f32 v167, v174, v175
	v_lshlrev_b32_e32 v174, 16, v168
	v_and_b32_e32 v175, 0xffff0000, v168
	v_pk_fma_f32 v[172:173], v[172:173], v[178:179], 1.0 op_sel_hi:[1,1,0] neg_lo:[1,0,0] neg_hi:[1,0,0]
	v_pk_mul_f32 v[174:175], v[94:95], v[174:175]
	v_pk_fma_f32 v[172:173], v[178:179], v[172:173], v[178:179]
	v_lshlrev_b32_e32 v168, 16, v169
	v_pk_mul_f32 v[172:173], v[172:173], v[174:175]
	v_pk_add_f32 v[174:175], v[180:181], 1.0 op_sel_hi:[1,0]
	v_and_b32_e32 v169, 0xffff0000, v169
	v_rcp_f32_e32 v178, v174
	v_rcp_f32_e32 v179, v175
	v_pk_mul_f32 v[168:169], v[96:97], v[168:169]
	v_max_f32_e64 v134, -v98, -v98
	v_min_f32_e32 v134, 0x42a00000, v134
	v_pk_fma_f32 v[174:175], v[174:175], v[178:179], 1.0 op_sel_hi:[1,1,0] neg_lo:[1,0,0] neg_hi:[1,0,0]
	v_mul_f32_e32 v134, 0x3fb8aa3b, v134
	v_pk_fma_f32 v[174:175], v[178:179], v[174:175], v[178:179]
	s_nop 0
	v_pk_mul_f32 v[174:175], v[174:175], v[168:169]
	v_cvt_pk_bf16_f32 v168, v172, v173
	v_cvt_pk_bf16_f32 v169, v174, v175
	v_or_b32_e32 v172, 48, v144
	global_store_dwordx4 v[170:171], v[166:169], off
	v_exp_f32_e32 v170, v134
	v_max_f32_e64 v134, -v99, -v99
	v_mad_i64_i32 v[166:167], s[26:27], v172, s50, v[146:147]
	v_lshl_add_u64 v[166:167], v[166:167], 0, v[142:143]
	v_mov_b32_e32 v166, v200
	v_mov_b32_e32 v167, v201
	v_mov_b32_e32 v168, v202
	v_mov_b32_e32 v169, v203
	v_min_f32_e32 v134, 0x42a00000, v134
	v_mul_f32_e32 v134, 0x3fb8aa3b, v134
	v_exp_f32_e32 v171, v134
	v_max_f32_e64 v134, -v100, -v100
	v_min_f32_e32 v134, 0x42a00000, v134
	v_mul_f32_e32 v134, 0x3fb8aa3b, v134
	v_pk_add_f32 v[170:171], v[170:171], 1.0 op_sel_hi:[1,0]
	v_exp_f32_e32 v180, v134
	v_max_f32_e64 v134, -v101, -v101
	v_rcp_f32_e32 v178, v170
	v_rcp_f32_e32 v179, v171
	v_min_f32_e32 v134, 0x42a00000, v134
	v_mul_f32_e32 v134, 0x3fb8aa3b, v134
	v_exp_f32_e32 v181, v134
	v_lshlrev_b32_e32 v174, 16, v162
	v_and_b32_e32 v175, 0xffff0000, v162
	v_pk_fma_f32 v[170:171], v[170:171], v[178:179], 1.0 op_sel_hi:[1,1,0] neg_lo:[1,0,0] neg_hi:[1,0,0]
	v_pk_mul_f32 v[174:175], v[106:107], v[174:175]
	v_pk_fma_f32 v[170:171], v[178:179], v[170:171], v[178:179]
	v_max_f32_e64 v134, -v74, -v74
	v_pk_mul_f32 v[170:171], v[170:171], v[174:175]
	v_pk_add_f32 v[174:175], v[180:181], 1.0 op_sel_hi:[1,0]
	v_lshlrev_b32_e32 v162, 16, v163
	v_rcp_f32_e32 v178, v174
	v_rcp_f32_e32 v179, v175
	v_and_b32_e32 v163, 0xffff0000, v163
	v_min_f32_e32 v134, 0x42a00000, v134
	v_pk_mul_f32 v[162:163], v[108:109], v[162:163]
	v_pk_fma_f32 v[174:175], v[174:175], v[178:179], 1.0 op_sel_hi:[1,1,0] neg_lo:[1,0,0] neg_hi:[1,0,0]
	v_mul_f32_e32 v134, 0x3fb8aa3b, v134
	v_pk_fma_f32 v[174:175], v[178:179], v[174:175], v[178:179]
	v_ashrrev_i32_e32 v173, 31, v172
	v_pk_mul_f32 v[174:175], v[174:175], v[162:163]
	v_cvt_pk_bf16_f32 v162, v170, v171
	v_exp_f32_e32 v170, v134
	v_max_f32_e64 v134, -v75, -v75
	v_min_f32_e32 v134, 0x42a00000, v134
	v_mul_f32_e32 v134, 0x3fb8aa3b, v134
	v_exp_f32_e32 v171, v134
	v_max_f32_e64 v134, -v76, -v76
	v_min_f32_e32 v134, 0x42a00000, v134
	v_mul_f32_e32 v134, 0x3fb8aa3b, v134
	v_pk_add_f32 v[170:171], v[170:171], 1.0 op_sel_hi:[1,0]
	v_exp_f32_e32 v180, v134
	v_max_f32_e64 v134, -v77, -v77
	v_rcp_f32_e32 v178, v170
	v_rcp_f32_e32 v179, v171
	v_min_f32_e32 v134, 0x42a00000, v134
	v_mul_f32_e32 v134, 0x3fb8aa3b, v134
	v_exp_f32_e32 v181, v134
	v_cvt_pk_bf16_f32 v163, v174, v175
	v_lshlrev_b32_e32 v174, 16, v164
	v_and_b32_e32 v175, 0xffff0000, v164
	v_pk_fma_f32 v[170:171], v[170:171], v[178:179], 1.0 op_sel_hi:[1,1,0] neg_lo:[1,0,0] neg_hi:[1,0,0]
	v_pk_mul_f32 v[174:175], v[78:79], v[174:175]
	v_pk_fma_f32 v[170:171], v[178:179], v[170:171], v[178:179]
	v_lshlrev_b32_e32 v164, 16, v165
	v_pk_mul_f32 v[170:171], v[170:171], v[174:175]
	v_pk_add_f32 v[174:175], v[180:181], 1.0 op_sel_hi:[1,0]
	v_and_b32_e32 v165, 0xffff0000, v165
	v_rcp_f32_e32 v178, v174
	v_rcp_f32_e32 v179, v175
	v_pk_mul_f32 v[164:165], v[80:81], v[164:165]
	v_max_f32_e64 v134, -v82, -v82
	v_min_f32_e32 v134, 0x42a00000, v134
; __device__ __forceinline__ float sigmoidf_(float x) { return rcp_nr(1.f + __expf(fminf(-x, 80.f))); }
; __device__ __forceinline__ u32x2 pk4(f32x4 v) { u32x2 r; r.x = pk2(v.x, v.y); r.y = pk2(v.z, v.w); return r; }
; __device__ __forceinline__ f32x4 unpk4(u32x2 w) { f32x4 r; r.x = bflo(w.x); r.y = bfhi(w.x); r.z = bflo(w.y); r.w = bfhi(w.y); return r; }
; template <int EPI>
; __device__ __forceinline__ void epilogue(const Params& p, f32x4 (&acc)[2][2][4][2], const int pm, const int pn, const int wr, const int wc, const int fr, const int fq) {
;     ...
;         for (int bj = 0; bj < 2; ++bj) {
;           const f32x4 ya = acc[ai][bj][m][0], yb = acc[ai][bj][m][1];
;           const f32x4 gs = unpk4(bj == 0 ? u32x2{gw4.x, gw4.y} : u32x2{gw4.z, gw4.w});
;           f32x4 sv;
;           sv.x = gs.x * ya.x * sigmoidf_(yb.x); sv.y = gs.y * ya.y * sigmoidf_(yb.y);
;           sv.z = gs.z * ya.z * sigmoidf_(yb.z); sv.w = gs.w * ya.w * sigmoidf_(yb.w);
;           o[bj] = pk4(sv);
;         }
;         *(u32x4*)(Mg + (size_t)row * DM + j0) = u32x4{o[0].x, o[0].y, o[1].x, o[1].y};
	v_pk_fma_f32 v[174:175], v[174:175], v[178:179], 1.0 op_sel_hi:[1,1,0] neg_lo:[1,0,0] neg_hi:[1,0,0]
	v_mul_f32_e32 v134, 0x3fb8aa3b, v134
	v_pk_fma_f32 v[174:175], v[178:179], v[174:175], v[178:179]
	s_nop 0
	v_pk_mul_f32 v[174:175], v[174:175], v[164:165]
	v_cvt_pk_bf16_f32 v164, v170, v171
	v_lshlrev_b64 v[170:171], 11, v[176:177]
	v_cvt_pk_bf16_f32 v165, v174, v175
	v_lshl_add_u64 v[170:171], v[148:149], 0, v[170:171]
	global_store_dwordx4 v[170:171], v[162:165], off
	s_nop 1
	v_exp_f32_e32 v162, v134
	v_max_f32_e64 v134, -v83, -v83
	v_min_f32_e32 v134, 0x42a00000, v134
	v_mul_f32_e32 v134, 0x3fb8aa3b, v134
	v_exp_f32_e32 v163, v134
	v_max_f32_e64 v134, -v84, -v84
	v_min_f32_e32 v134, 0x42a00000, v134
	v_mul_f32_e32 v134, 0x3fb8aa3b, v134
	v_pk_add_f32 v[162:163], v[162:163], 1.0 op_sel_hi:[1,0]
	v_exp_f32_e32 v174, v134
	v_max_f32_e64 v134, -v85, -v85
	v_rcp_f32_e32 v170, v162
	v_rcp_f32_e32 v171, v163
	v_min_f32_e32 v134, 0x42a00000, v134
	v_mul_f32_e32 v134, 0x3fb8aa3b, v134
	v_exp_f32_e32 v175, v134
	v_lshlrev_b32_e32 v164, 16, v166
	v_and_b32_e32 v165, 0xffff0000, v166
	v_pk_fma_f32 v[162:163], v[162:163], v[170:171], 1.0 op_sel_hi:[1,1,0] neg_lo:[1,0,0] neg_hi:[1,0,0]
	v_pk_mul_f32 v[164:165], v[90:91], v[164:165]
	v_pk_fma_f32 v[162:163], v[170:171], v[162:163], v[170:171]
	v_max_f32_e64 v134, -v66, -v66
	v_pk_mul_f32 v[162:163], v[162:163], v[164:165]
	v_pk_add_f32 v[164:165], v[174:175], 1.0 op_sel_hi:[1,0]
	v_lshlrev_b32_e32 v166, 16, v167
	v_rcp_f32_e32 v170, v164
	v_rcp_f32_e32 v171, v165
	v_and_b32_e32 v167, 0xffff0000, v167
	v_min_f32_e32 v134, 0x42a00000, v134
	v_pk_mul_f32 v[166:167], v[92:93], v[166:167]
	v_pk_fma_f32 v[164:165], v[164:165], v[170:171], 1.0 op_sel_hi:[1,1,0] neg_lo:[1,0,0] neg_hi:[1,0,0]
	v_mul_f32_e32 v134, 0x3fb8aa3b, v134
	v_pk_fma_f32 v[164:165], v[170:171], v[164:165], v[170:171]
	v_cvt_pk_bf16_f32 v162, v162, v163
	v_pk_mul_f32 v[164:165], v[164:165], v[166:167]
	v_exp_f32_e32 v166, v134
	v_max_f32_e64 v134, -v67, -v67
	v_min_f32_e32 v134, 0x42a00000, v134
	v_mul_f32_e32 v134, 0x3fb8aa3b, v134
	v_exp_f32_e32 v167, v134
	v_max_f32_e64 v134, -v68, -v68
	v_min_f32_e32 v134, 0x42a00000, v134
	v_mul_f32_e32 v134, 0x3fb8aa3b, v134
	v_pk_add_f32 v[166:167], v[166:167], 1.0 op_sel_hi:[1,0]
	v_exp_f32_e32 v174, v134
	v_max_f32_e64 v134, -v69, -v69
	v_rcp_f32_e32 v170, v166
	v_rcp_f32_e32 v171, v167
	v_min_f32_e32 v134, 0x42a00000, v134
	v_mul_f32_e32 v134, 0x3fb8aa3b, v134
	v_exp_f32_e32 v175, v134
	v_cvt_pk_bf16_f32 v163, v164, v165
	v_lshlrev_b32_e32 v164, 16, v168
	v_and_b32_e32 v165, 0xffff0000, v168
	v_pk_fma_f32 v[166:167], v[166:167], v[170:171], 1.0 op_sel_hi:[1,1,0] neg_lo:[1,0,0] neg_hi:[1,0,0]
	v_pk_mul_f32 v[164:165], v[70:71], v[164:165]
	v_pk_fma_f32 v[166:167], v[170:171], v[166:167], v[170:171]
	v_lshlrev_b32_e32 v168, 16, v169
	v_pk_mul_f32 v[164:165], v[166:167], v[164:165]
	v_pk_add_f32 v[166:167], v[174:175], 1.0 op_sel_hi:[1,0]
	v_and_b32_e32 v169, 0xffff0000, v169
	v_rcp_f32_e32 v170, v166
	v_rcp_f32_e32 v171, v167
	v_pk_mul_f32 v[168:169], v[72:73], v[168:169]
	v_cvt_pk_bf16_f32 v164, v164, v165
	v_max_f32_e64 v134, -v58, -v58
	v_pk_fma_f32 v[166:167], v[166:167], v[170:171], 1.0 op_sel_hi:[1,1,0] neg_lo:[1,0,0] neg_hi:[1,0,0]
	v_min_f32_e32 v134, 0x42a00000, v134
	v_pk_fma_f32 v[166:167], v[170:171], v[166:167], v[170:171]
	v_mul_f32_e32 v134, 0x3fb8aa3b, v134
	v_pk_mul_f32 v[166:167], v[166:167], v[168:169]
	v_exp_f32_e32 v168, v134
	v_cvt_pk_bf16_f32 v165, v166, v167
	v_lshlrev_b64 v[166:167], 11, v[172:173]
	v_lshl_add_u64 v[166:167], v[148:149], 0, v[166:167]
	global_store_dwordx4 v[166:167], v[162:165], off
	v_add_u32_e32 v166, 0x80, v144
	v_max_f32_e64 v134, -v59, -v59
	v_mad_i64_i32 v[162:163], s[26:27], v166, s50, v[146:147]
	v_lshl_add_u64 v[162:163], v[162:163], 0, v[142:143]
	v_mov_b32_e32 v162, v204
	v_mov_b32_e32 v163, v205
	v_mov_b32_e32 v164, v206
	v_mov_b32_e32 v165, v207
	v_min_f32_e32 v134, 0x42a00000, v134
	v_mul_f32_e32 v134, 0x3fb8aa3b, v134
	v_exp_f32_e32 v169, v134
	v_max_f32_e64 v134, -v60, -v60
	v_min_f32_e32 v134, 0x42a00000, v134
	v_mul_f32_e32 v134, 0x3fb8aa3b, v134
	v_pk_add_f32 v[168:169], v[168:169], 1.0 op_sel_hi:[1,0]
	v_exp_f32_e32 v174, v134
	v_max_f32_e64 v134, -v61, -v61
	v_rcp_f32_e32 v172, v168
	v_rcp_f32_e32 v173, v169
	v_min_f32_e32 v134, 0x42a00000, v134
	v_mul_f32_e32 v134, 0x3fb8aa3b, v134
	v_exp_f32_e32 v175, v134
	v_pk_fma_f32 v[168:169], v[168:169], v[172:173], 1.0 op_sel_hi:[1,1,0] neg_lo:[1,0,0] neg_hi:[1,0,0]
	v_max_f32_e64 v134, -v38, -v38
	v_pk_fma_f32 v[168:169], v[172:173], v[168:169], v[172:173]
	v_min_f32_e32 v134, 0x42a00000, v134
	v_mul_f32_e32 v134, 0x3fb8aa3b, v134
	v_ashrrev_i32_e32 v167, 31, v166
	v_lshlrev_b64 v[166:167], 11, v[166:167]
	v_lshl_add_u64 v[166:167], v[148:149], 0, v[166:167]
	v_lshlrev_b32_e32 v170, 16, v162
	v_and_b32_e32 v171, 0xffff0000, v162
	v_pk_mul_f32 v[170:171], v[62:63], v[170:171]
	v_lshlrev_b32_e32 v162, 16, v163
	v_pk_mul_f32 v[168:169], v[168:169], v[170:171]
	v_pk_add_f32 v[170:171], v[174:175], 1.0 op_sel_hi:[1,0]
	v_and_b32_e32 v163, 0xffff0000, v163
	v_rcp_f32_e32 v172, v170
	v_rcp_f32_e32 v173, v171
	v_pk_mul_f32 v[162:163], v[64:65], v[162:163]
	v_pk_fma_f32 v[170:171], v[170:171], v[172:173], 1.0 op_sel_hi:[1,1,0] neg_lo:[1,0,0] neg_hi:[1,0,0]
	s_nop 0
	v_pk_fma_f32 v[170:171], v[172:173], v[170:171], v[172:173]
	s_nop 0
	v_pk_mul_f32 v[170:171], v[170:171], v[162:163]
	v_cvt_pk_bf16_f32 v162, v168, v169
	v_exp_f32_e32 v168, v134
	v_max_f32_e64 v134, -v39, -v39
	v_min_f32_e32 v134, 0x42a00000, v134
	v_mul_f32_e32 v134, 0x3fb8aa3b, v134
	v_exp_f32_e32 v169, v134
	v_max_f32_e64 v134, -v40, -v40
; __device__ __forceinline__ float sigmoidf_(float x) { return rcp_nr(1.f + __expf(fminf(-x, 80.f))); }
; __device__ __forceinline__ u32x2 pk4(f32x4 v) { u32x2 r; r.x = pk2(v.x, v.y); r.y = pk2(v.z, v.w); return r; }
; __device__ __forceinline__ f32x4 unpk4(u32x2 w) { f32x4 r; r.x = bflo(w.x); r.y = bfhi(w.x); r.z = bflo(w.y); r.w = bfhi(w.y); return r; }
; template <int EPI>
; __device__ __forceinline__ void epilogue(const Params& p, f32x4 (&acc)[2][2][4][2], const int pm, const int pn, const int wr, const int wc, const int fr, const int fq) {
;     ...
;         for (int bj = 0; bj < 2; ++bj) {
;           const f32x4 ya = acc[ai][bj][m][0], yb = acc[ai][bj][m][1];
;           const f32x4 gs = unpk4(bj == 0 ? u32x2{gw4.x, gw4.y} : u32x2{gw4.z, gw4.w});
;           f32x4 sv;
;           sv.x = gs.x * ya.x * sigmoidf_(yb.x); sv.y = gs.y * ya.y * sigmoidf_(yb.y);
;           sv.z = gs.z * ya.z * sigmoidf_(yb.z); sv.w = gs.w * ya.w * sigmoidf_(yb.w);
;           o[bj] = pk4(sv);
;         }
;         *(u32x4*)(Mg + (size_t)row * DM + j0) = u32x4{o[0].x, o[0].y, o[1].x, o[1].y};
	v_min_f32_e32 v134, 0x42a00000, v134
	v_mul_f32_e32 v134, 0x3fb8aa3b, v134
	v_pk_add_f32 v[168:169], v[168:169], 1.0 op_sel_hi:[1,0]
	v_exp_f32_e32 v174, v134
	v_max_f32_e64 v134, -v41, -v41
	v_rcp_f32_e32 v172, v168
	v_rcp_f32_e32 v173, v169
	v_min_f32_e32 v134, 0x42a00000, v134
	v_mul_f32_e32 v134, 0x3fb8aa3b, v134
	v_exp_f32_e32 v175, v134
	v_cvt_pk_bf16_f32 v163, v170, v171
	v_lshlrev_b32_e32 v170, 16, v164
	v_and_b32_e32 v171, 0xffff0000, v164
	v_pk_fma_f32 v[168:169], v[168:169], v[172:173], 1.0 op_sel_hi:[1,1,0] neg_lo:[1,0,0] neg_hi:[1,0,0]
	v_pk_mul_f32 v[170:171], v[46:47], v[170:171]
	v_pk_fma_f32 v[168:169], v[172:173], v[168:169], v[172:173]
	v_lshlrev_b32_e32 v164, 16, v165
	v_pk_mul_f32 v[168:169], v[168:169], v[170:171]
	v_pk_add_f32 v[170:171], v[174:175], 1.0 op_sel_hi:[1,0]
	v_and_b32_e32 v165, 0xffff0000, v165
	v_rcp_f32_e32 v172, v170
	v_rcp_f32_e32 v173, v171
	v_pk_mul_f32 v[164:165], v[48:49], v[164:165]
	v_max_f32_e64 v134, -v50, -v50
	v_min_f32_e32 v134, 0x42a00000, v134
	v_pk_fma_f32 v[170:171], v[170:171], v[172:173], 1.0 op_sel_hi:[1,1,0] neg_lo:[1,0,0] neg_hi:[1,0,0]
	v_mul_f32_e32 v134, 0x3fb8aa3b, v134
	v_pk_fma_f32 v[170:171], v[172:173], v[170:171], v[172:173]
	s_nop 0
	v_pk_mul_f32 v[170:171], v[170:171], v[164:165]
	v_cvt_pk_bf16_f32 v164, v168, v169
	v_cvt_pk_bf16_f32 v165, v170, v171
	global_store_dwordx4 v[166:167], v[162:165], off
	v_add_u32_e32 v166, 0x90, v144
	v_exp_f32_e32 v168, v134
	v_mad_i64_i32 v[162:163], s[26:27], v166, s50, v[146:147]
	v_lshl_add_u64 v[162:163], v[162:163], 0, v[142:143]
	v_mov_b32_e32 v162, v208
	v_mov_b32_e32 v163, v209
	v_mov_b32_e32 v164, v210
	v_mov_b32_e32 v165, v211
	v_max_f32_e64 v134, -v51, -v51
	v_min_f32_e32 v134, 0x42a00000, v134
	v_mul_f32_e32 v134, 0x3fb8aa3b, v134
	v_exp_f32_e32 v169, v134
	v_max_f32_e64 v134, -v52, -v52
	v_min_f32_e32 v134, 0x42a00000, v134
	v_mul_f32_e32 v134, 0x3fb8aa3b, v134
	v_pk_add_f32 v[168:169], v[168:169], 1.0 op_sel_hi:[1,0]
	v_exp_f32_e32 v174, v134
	v_max_f32_e64 v134, -v53, -v53
	v_rcp_f32_e32 v172, v168
	v_rcp_f32_e32 v173, v169
	v_min_f32_e32 v134, 0x42a00000, v134
	v_mul_f32_e32 v134, 0x3fb8aa3b, v134
	v_exp_f32_e32 v175, v134
	v_pk_fma_f32 v[168:169], v[168:169], v[172:173], 1.0 op_sel_hi:[1,1,0] neg_lo:[1,0,0] neg_hi:[1,0,0]
	v_max_f32_e64 v134, -v22, -v22
	v_pk_fma_f32 v[168:169], v[172:173], v[168:169], v[172:173]
	v_min_f32_e32 v134, 0x42a00000, v134
	v_mul_f32_e32 v134, 0x3fb8aa3b, v134
	v_ashrrev_i32_e32 v167, 31, v166
	v_lshlrev_b64 v[166:167], 11, v[166:167]
	v_lshl_add_u64 v[166:167], v[148:149], 0, v[166:167]
	v_lshlrev_b32_e32 v170, 16, v162
	v_and_b32_e32 v171, 0xffff0000, v162
	v_pk_mul_f32 v[170:171], v[54:55], v[170:171]
	v_lshlrev_b32_e32 v162, 16, v163
	v_pk_mul_f32 v[168:169], v[168:169], v[170:171]
	v_pk_add_f32 v[170:171], v[174:175], 1.0 op_sel_hi:[1,0]
	v_and_b32_e32 v163, 0xffff0000, v163
	v_rcp_f32_e32 v172, v170
	v_rcp_f32_e32 v173, v171
	v_pk_mul_f32 v[162:163], v[56:57], v[162:163]
	v_pk_fma_f32 v[170:171], v[170:171], v[172:173], 1.0 op_sel_hi:[1,1,0] neg_lo:[1,0,0] neg_hi:[1,0,0]
	s_nop 0
	v_pk_fma_f32 v[170:171], v[172:173], v[170:171], v[172:173]
	s_nop 0
	v_pk_mul_f32 v[170:171], v[170:171], v[162:163]
	v_cvt_pk_bf16_f32 v162, v168, v169
	v_exp_f32_e32 v168, v134
	v_max_f32_e64 v134, -v23, -v23
	v_min_f32_e32 v134, 0x42a00000, v134
	v_mul_f32_e32 v134, 0x3fb8aa3b, v134
	v_exp_f32_e32 v169, v134
	v_max_f32_e64 v134, -v24, -v24
	v_min_f32_e32 v134, 0x42a00000, v134
	v_mul_f32_e32 v134, 0x3fb8aa3b, v134
	v_pk_add_f32 v[168:169], v[168:169], 1.0 op_sel_hi:[1,0]
	v_exp_f32_e32 v174, v134
	v_max_f32_e64 v134, -v25, -v25
	v_rcp_f32_e32 v172, v168
	v_rcp_f32_e32 v173, v169
	v_min_f32_e32 v134, 0x42a00000, v134
	v_mul_f32_e32 v134, 0x3fb8aa3b, v134
	v_exp_f32_e32 v175, v134
	v_cvt_pk_bf16_f32 v163, v170, v171
	v_lshlrev_b32_e32 v170, 16, v164
	v_and_b32_e32 v171, 0xffff0000, v164
	v_pk_fma_f32 v[168:169], v[168:169], v[172:173], 1.0 op_sel_hi:[1,1,0] neg_lo:[1,0,0] neg_hi:[1,0,0]
	v_pk_mul_f32 v[170:171], v[30:31], v[170:171]
	v_pk_fma_f32 v[168:169], v[172:173], v[168:169], v[172:173]
	v_lshlrev_b32_e32 v164, 16, v165
	v_pk_mul_f32 v[168:169], v[168:169], v[170:171]
	v_pk_add_f32 v[170:171], v[174:175], 1.0 op_sel_hi:[1,0]
	v_and_b32_e32 v165, 0xffff0000, v165
	v_rcp_f32_e32 v172, v170
	v_rcp_f32_e32 v173, v171
	v_pk_mul_f32 v[164:165], v[32:33], v[164:165]
	v_max_f32_e64 v134, -v34, -v34
	v_min_f32_e32 v134, 0x42a00000, v134
	v_pk_fma_f32 v[170:171], v[170:171], v[172:173], 1.0 op_sel_hi:[1,1,0] neg_lo:[1,0,0] neg_hi:[1,0,0]
	v_mul_f32_e32 v134, 0x3fb8aa3b, v134
	v_pk_fma_f32 v[170:171], v[172:173], v[170:171], v[172:173]
	s_nop 0
	v_pk_mul_f32 v[170:171], v[170:171], v[164:165]
	v_cvt_pk_bf16_f32 v164, v168, v169
	v_cvt_pk_bf16_f32 v165, v170, v171
	global_store_dwordx4 v[166:167], v[162:165], off
	v_add_u32_e32 v166, 0xa0, v144
	v_exp_f32_e32 v168, v134
	v_mad_i64_i32 v[162:163], s[26:27], v166, s50, v[146:147]
	v_lshl_add_u64 v[162:163], v[162:163], 0, v[142:143]
	v_mov_b32_e32 v162, v212
	v_mov_b32_e32 v163, v213
	v_mov_b32_e32 v164, v214
	v_mov_b32_e32 v165, v215
	v_max_f32_e64 v134, -v35, -v35
	v_min_f32_e32 v134, 0x42a00000, v134
	v_mul_f32_e32 v134, 0x3fb8aa3b, v134
	v_exp_f32_e32 v169, v134
	v_max_f32_e64 v134, -v36, -v36
	v_min_f32_e32 v134, 0x42a00000, v134
	v_mul_f32_e32 v134, 0x3fb8aa3b, v134
	v_pk_add_f32 v[168:169], v[168:169], 1.0 op_sel_hi:[1,0]
	v_exp_f32_e32 v174, v134
	v_max_f32_e64 v134, -v37, -v37
	v_rcp_f32_e32 v172, v168
	v_rcp_f32_e32 v173, v169
	v_min_f32_e32 v134, 0x42a00000, v134
	v_mul_f32_e32 v134, 0x3fb8aa3b, v134
	v_exp_f32_e32 v175, v134
; __device__ __forceinline__ float sigmoidf_(float x) { return rcp_nr(1.f + __expf(fminf(-x, 80.f))); }
; __device__ __forceinline__ u32x2 pk4(f32x4 v) { u32x2 r; r.x = pk2(v.x, v.y); r.y = pk2(v.z, v.w); return r; }
; __device__ __forceinline__ f32x4 unpk4(u32x2 w) { f32x4 r; r.x = bflo(w.x); r.y = bfhi(w.x); r.z = bflo(w.y); r.w = bfhi(w.y); return r; }
; template <int EPI>
; __device__ __forceinline__ void epilogue(const Params& p, f32x4 (&acc)[2][2][4][2], const int pm, const int pn, const int wr, const int wc, const int fr, const int fq) {
;     ...
;         for (int bj = 0; bj < 2; ++bj) {
;           const f32x4 ya = acc[ai][bj][m][0], yb = acc[ai][bj][m][1];
;           const f32x4 gs = unpk4(bj == 0 ? u32x2{gw4.x, gw4.y} : u32x2{gw4.z, gw4.w});
;           f32x4 sv;
;           sv.x = gs.x * ya.x * sigmoidf_(yb.x); sv.y = gs.y * ya.y * sigmoidf_(yb.y);
;           sv.z = gs.z * ya.z * sigmoidf_(yb.z); sv.w = gs.w * ya.w * sigmoidf_(yb.w);
;           o[bj] = pk4(sv);
;         }
;         *(u32x4*)(Mg + (size_t)row * DM + j0) = u32x4{o[0].x, o[0].y, o[1].x, o[1].y};
;       }
	v_pk_fma_f32 v[168:169], v[168:169], v[172:173], 1.0 op_sel_hi:[1,1,0] neg_lo:[1,0,0] neg_hi:[1,0,0]
	v_max_f32_e64 v134, -v10, -v10
	v_pk_fma_f32 v[168:169], v[172:173], v[168:169], v[172:173]
	v_min_f32_e32 v134, 0x42a00000, v134
	v_mul_f32_e32 v134, 0x3fb8aa3b, v134
	v_ashrrev_i32_e32 v167, 31, v166
	v_lshlrev_b64 v[166:167], 11, v[166:167]
	v_lshl_add_u64 v[166:167], v[148:149], 0, v[166:167]
	v_lshlrev_b32_e32 v170, 16, v162
	v_and_b32_e32 v171, 0xffff0000, v162
	v_pk_mul_f32 v[170:171], v[42:43], v[170:171]
	v_lshlrev_b32_e32 v162, 16, v163
	v_pk_mul_f32 v[168:169], v[168:169], v[170:171]
	v_pk_add_f32 v[170:171], v[174:175], 1.0 op_sel_hi:[1,0]
	v_and_b32_e32 v163, 0xffff0000, v163
	v_rcp_f32_e32 v172, v170
	v_rcp_f32_e32 v173, v171
	v_pk_mul_f32 v[162:163], v[44:45], v[162:163]
	v_pk_fma_f32 v[170:171], v[170:171], v[172:173], 1.0 op_sel_hi:[1,1,0] neg_lo:[1,0,0] neg_hi:[1,0,0]
	s_nop 0
	v_pk_fma_f32 v[170:171], v[172:173], v[170:171], v[172:173]
	s_nop 0
	v_pk_mul_f32 v[170:171], v[170:171], v[162:163]
	v_cvt_pk_bf16_f32 v162, v168, v169
	v_exp_f32_e32 v168, v134
	v_max_f32_e64 v134, -v11, -v11
	v_min_f32_e32 v134, 0x42a00000, v134
	v_mul_f32_e32 v134, 0x3fb8aa3b, v134
	v_exp_f32_e32 v169, v134
	v_max_f32_e64 v134, -v12, -v12
	v_min_f32_e32 v134, 0x42a00000, v134
	v_mul_f32_e32 v134, 0x3fb8aa3b, v134
	v_pk_add_f32 v[168:169], v[168:169], 1.0 op_sel_hi:[1,0]
	v_exp_f32_e32 v174, v134
	v_max_f32_e64 v134, -v13, -v13
	v_rcp_f32_e32 v172, v168
	v_rcp_f32_e32 v173, v169
	v_min_f32_e32 v134, 0x42a00000, v134
	v_mul_f32_e32 v134, 0x3fb8aa3b, v134
	v_exp_f32_e32 v175, v134
	v_cvt_pk_bf16_f32 v163, v170, v171
	v_lshlrev_b32_e32 v170, 16, v164
	v_and_b32_e32 v171, 0xffff0000, v164
	v_pk_fma_f32 v[168:169], v[168:169], v[172:173], 1.0 op_sel_hi:[1,1,0] neg_lo:[1,0,0] neg_hi:[1,0,0]
	v_pk_mul_f32 v[170:171], v[14:15], v[170:171]
	v_pk_fma_f32 v[168:169], v[172:173], v[168:169], v[172:173]
	v_lshlrev_b32_e32 v164, 16, v165
	v_pk_mul_f32 v[168:169], v[168:169], v[170:171]
	v_pk_add_f32 v[170:171], v[174:175], 1.0 op_sel_hi:[1,0]
	v_and_b32_e32 v165, 0xffff0000, v165
	v_rcp_f32_e32 v172, v170
	v_rcp_f32_e32 v173, v171
	v_pk_mul_f32 v[164:165], v[16:17], v[164:165]
	v_max_f32_e64 v134, -v18, -v18
	v_min_f32_e32 v134, 0x42a00000, v134
	v_pk_fma_f32 v[170:171], v[170:171], v[172:173], 1.0 op_sel_hi:[1,1,0] neg_lo:[1,0,0] neg_hi:[1,0,0]
	v_mul_f32_e32 v134, 0x3fb8aa3b, v134
	v_pk_fma_f32 v[170:171], v[172:173], v[170:171], v[172:173]
	s_nop 0
	v_pk_mul_f32 v[170:171], v[170:171], v[164:165]
	v_cvt_pk_bf16_f32 v164, v168, v169
	v_cvt_pk_bf16_f32 v165, v170, v171
	global_store_dwordx4 v[166:167], v[162:165], off
	s_nop 1
	v_add_u32_e32 v162, 0xb0, v144
	v_mad_i64_i32 v[144:145], s[26:27], v162, s50, v[146:147]
	v_lshl_add_u64 v[142:143], v[144:145], 0, v[142:143]
	v_mov_b32_e32 v142, v216
	v_mov_b32_e32 v143, v217
	v_mov_b32_e32 v144, v218
	v_mov_b32_e32 v145, v219
	v_exp_f32_e32 v146, v134
	v_max_f32_e64 v134, -v19, -v19
	v_min_f32_e32 v134, 0x42a00000, v134
	v_mul_f32_e32 v134, 0x3fb8aa3b, v134
	v_exp_f32_e32 v147, v134
	v_max_f32_e64 v134, -v20, -v20
	v_min_f32_e32 v134, 0x42a00000, v134
	v_mul_f32_e32 v134, 0x3fb8aa3b, v134
	v_pk_add_f32 v[146:147], v[146:147], 1.0 op_sel_hi:[1,0]
	v_exp_f32_e32 v168, v134
	v_max_f32_e64 v134, -v21, -v21
	v_rcp_f32_e32 v166, v146
	v_rcp_f32_e32 v167, v147
	v_min_f32_e32 v134, 0x42a00000, v134
	v_mul_f32_e32 v134, 0x3fb8aa3b, v134
	v_exp_f32_e32 v169, v134
	v_pk_fma_f32 v[146:147], v[146:147], v[166:167], 1.0 op_sel_hi:[1,1,0] neg_lo:[1,0,0] neg_hi:[1,0,0]
	v_max_f32_e64 v134, -v2, -v2
	v_pk_fma_f32 v[146:147], v[166:167], v[146:147], v[166:167]
	v_min_f32_e32 v134, 0x42a00000, v134
	v_mul_f32_e32 v134, 0x3fb8aa3b, v134
	v_ashrrev_i32_e32 v163, 31, v162
	v_lshlrev_b32_e32 v164, 16, v142
	v_and_b32_e32 v165, 0xffff0000, v142
	v_pk_mul_f32 v[164:165], v[26:27], v[164:165]
	v_lshlrev_b32_e32 v142, 16, v143
	v_pk_mul_f32 v[146:147], v[146:147], v[164:165]
	v_pk_add_f32 v[164:165], v[168:169], 1.0 op_sel_hi:[1,0]
	v_and_b32_e32 v143, 0xffff0000, v143
	v_rcp_f32_e32 v166, v164
	v_rcp_f32_e32 v167, v165
	v_pk_mul_f32 v[142:143], v[28:29], v[142:143]
	v_pk_fma_f32 v[164:165], v[164:165], v[166:167], 1.0 op_sel_hi:[1,1,0] neg_lo:[1,0,0] neg_hi:[1,0,0]
	s_nop 0
	v_pk_fma_f32 v[164:165], v[166:167], v[164:165], v[166:167]
	s_nop 0
	v_pk_mul_f32 v[164:165], v[164:165], v[142:143]
	v_cvt_pk_bf16_f32 v142, v146, v147
	v_exp_f32_e32 v146, v134
	v_max_f32_e64 v134, -v3, -v3
	v_min_f32_e32 v134, 0x42a00000, v134
	v_mul_f32_e32 v134, 0x3fb8aa3b, v134
	v_exp_f32_e32 v147, v134
	v_max_f32_e64 v134, -v4, -v4
	v_min_f32_e32 v134, 0x42a00000, v134
	v_mul_f32_e32 v134, 0x3fb8aa3b, v134
	v_pk_add_f32 v[146:147], v[146:147], 1.0 op_sel_hi:[1,0]
	v_exp_f32_e32 v168, v134
	v_max_f32_e64 v134, -v5, -v5
	v_rcp_f32_e32 v166, v146
	v_rcp_f32_e32 v167, v147
	v_min_f32_e32 v134, 0x42a00000, v134
	v_mul_f32_e32 v134, 0x3fb8aa3b, v134
	v_exp_f32_e32 v169, v134
	v_cvt_pk_bf16_f32 v143, v164, v165
	v_lshlrev_b32_e32 v164, 16, v144
	v_and_b32_e32 v165, 0xffff0000, v144
	v_pk_fma_f32 v[146:147], v[146:147], v[166:167], 1.0 op_sel_hi:[1,1,0] neg_lo:[1,0,0] neg_hi:[1,0,0]
	v_pk_mul_f32 v[164:165], v[6:7], v[164:165]
	v_pk_fma_f32 v[146:147], v[166:167], v[146:147], v[166:167]
	v_lshlrev_b32_e32 v144, 16, v145
	v_pk_mul_f32 v[146:147], v[146:147], v[164:165]
	v_pk_add_f32 v[164:165], v[168:169], 1.0 op_sel_hi:[1,0]
	v_and_b32_e32 v145, 0xffff0000, v145
	v_rcp_f32_e32 v166, v164
	v_rcp_f32_e32 v167, v165
	v_pk_mul_f32 v[144:145], v[8:9], v[144:145]
	v_pk_fma_f32 v[164:165], v[164:165], v[166:167], 1.0 op_sel_hi:[1,1,0] neg_lo:[1,0,0] neg_hi:[1,0,0]
	s_nop 0
	v_pk_fma_f32 v[164:165], v[166:167], v[164:165], v[166:167]
	s_nop 0
	v_pk_mul_f32 v[164:165], v[164:165], v[144:145]
	v_cvt_pk_bf16_f32 v144, v146, v147
	v_lshlrev_b64 v[146:147], 11, v[162:163]
	v_cvt_pk_bf16_f32 v145, v164, v165
	v_lshl_add_u64 v[146:147], v[148:149], 0, v[146:147]
	global_store_dwordx4 v[146:147], v[142:145], off
	s_cbranch_execz .LBB0_660
